# FFN-up phases: the 6 percent idle-slot weight-preparation share of the second six-tile workgroup group moved to the five-tile groups (the six-tile groups are the critical path now)
# speedup vs baseline: 1.0013x; 1.0013x over previous
.LBB0_149:
	s_cmp_eq_u32 s2, 1
	s_cselect_b64 s[8:9], -1, 0
	s_cmp_lg_u32 s2, 1
	s_cselect_b64 s[0:1], -1, 0
	s_cmp_eq_u32 s2, 6
	s_cselect_b64 s[4:5], -1, 0
	s_and_b64 s[4:5], s[4:5], s[22:23]
	s_or_b64 s[4:5], s[8:9], s[4:5]
	s_andn2_b64 vcc, exec, s[4:5]
	s_mov_b64 s[68:69], 0
	s_cbranch_vccnz .LBB0_208
	s_cmpk_lg_i32 s33, 0x100
	s_cselect_b64 s[4:5], -1, 0
	s_and_b64 s[68:69], s[8:9], s[88:89]
	s_or_b64 s[4:5], s[4:5], s[68:69]
	s_mov_b32 s74, s29
	s_and_b64 vcc, exec, s[4:5]
	s_movk_i32 s28, 0x3000
	s_movk_i32 s29, 0x430
	s_movk_i32 s35, 0x10c0
	s_movk_i32 s39, 0xc00
	s_cbranch_vccnz .LBB0_152
	s_and_b64 s[4:5], exec, s[26:27]
	s_movk_i32 s3, 0x780
	s_movk_i32 s4, 0x4c0
	s_cselect_b32 s3, s3, 0x580
	s_cselect_b32 s6, s4, 0x3e0
	s_and_b64 s[4:5], s[8:9], exec
	s_cselect_b32 s3, s3, s6
	s_mul_i32 s5, s3, 0x7ae2
	s_ashr_i32 s4, s79, 6
	s_mov_b32 s10, 0
	s_lshr_b32 s3, s3, 1
	s_cmp_eq_u32 s4, 2
	s_cselect_b32 s12, s10, s3
	s_cselect_b32 s3, s3, 0x7fffffff
	s_cmp_eq_u32 s4, 1
	s_cselect_b64 s[4:5], -1, 0
	s_and_b64 s[6:7], s[4:5], exec
	s_cselect_b32 s3, s10, s3
	s_cmp_lt_u32 s79, 64
	s_cselect_b64 s[6:7], -1, 0
	s_and_b64 s[10:11], s[6:7], exec
	s_cselect_b32 s15, 0, s3
	s_or_b64 s[4:5], s[6:7], s[4:5]
	s_and_b64 s[4:5], s[4:5], exec
	s_mov_b32 s14, 64
	s_cselect_b32 s18, 0, s12
	s_and_b32 s19, s79, 63
	s_mov_b64 s[4:5], -1
	s_and_b64 vcc, exec, s[0:1]
	s_cbranch_vccnz .LBB0_153
	s_branch .LBB0_180
